# in-projection K-loop: loop-control and pointer-select SALU hoisted from the loader segment into the last MFMA segment
# speedup vs baseline: 1.0165x; 1.0008x over previous
.Lk367_body:
	v_add_u32_e32 v154, s53, v144
	v_add_u32_e32 v170, s90, v144
	ds_read_b128 v[140:143], v154
	ds_read_b128 v[146:149], v154 offset:1024
	ds_read_b128 v[150:153], v154 offset:2048
	ds_read_b128 v[154:157], v154 offset:3072
	ds_read_b128 v[158:161], v170
	ds_read_b128 v[162:165], v170 offset:1024
	ds_read_b128 v[166:169], v170 offset:2048
	ds_read_b128 v[170:173], v170 offset:3072
	s_add_u32 s96, s4, 0xfff00000
	s_addc_u32 s97, s5, -1
	s_mov_b32 m0, s51
	s_nop 0
	global_load_lds_dwordx4 v128, s[96:97]
	s_mov_b32 m0, s52
	s_nop 0
	global_load_lds_dwordx4 v132, s[96:97]
	s_add_i32 m0, s49, 0xc000
	ds_read_b128 v[188:191], v145
	ds_read_b128 v[192:195], v145 offset:1024
	ds_read_b128 v[196:199], v145 offset:2048
	ds_read_b128 v[200:203], v145 offset:3072
	ds_read_b128 v[204:207], v145 offset:4096
	ds_read_b128 v[208:211], v145 offset:5120
	ds_read_b128 v[212:215], v145 offset:6144
	ds_read_b128 v[216:219], v145 offset:7168
	global_load_lds_dwordx4 v136, s[4:5]
	s_add_i32 m0, s49, 0xe000
	s_nop 0
	global_load_lds_dwordx4 v138, s[4:5]
	s_waitcnt vmcnt(8)
	s_waitcnt lgkmcnt(0)
	s_barrier
	s_setprio 1
	s_waitcnt lgkmcnt(0)
	v_mfma_f32_16x16x32_bf16 v[124:127], v[140:143], v[188:191], v[124:127]
	v_mfma_f32_16x16x32_bf16 v[120:123], v[150:153], v[188:191], v[120:123]
	v_mfma_f32_16x16x32_bf16 v[108:111], v[140:143], v[196:199], v[108:111]
	v_mfma_f32_16x16x32_bf16 v[104:107], v[150:153], v[196:199], v[104:107]
	v_mfma_f32_16x16x32_bf16 v[92:95], v[140:143], v[204:207], v[92:95]
	v_mfma_f32_16x16x32_bf16 v[88:91], v[150:153], v[204:207], v[88:91]
	v_mfma_f32_16x16x32_bf16 v[76:79], v[140:143], v[212:215], v[76:79]
	v_mfma_f32_16x16x32_bf16 v[72:75], v[150:153], v[212:215], v[72:75]
	v_mfma_f32_16x16x32_bf16 v[124:127], v[146:149], v[192:195], v[124:127]
	v_mfma_f32_16x16x32_bf16 v[120:123], v[154:157], v[192:195], v[120:123]
	v_mfma_f32_16x16x32_bf16 v[108:111], v[146:149], v[200:203], v[108:111]
	v_mfma_f32_16x16x32_bf16 v[104:107], v[154:157], v[200:203], v[104:107]
	v_mfma_f32_16x16x32_bf16 v[92:95], v[146:149], v[208:211], v[92:95]
	v_mfma_f32_16x16x32_bf16 v[88:91], v[154:157], v[208:211], v[88:91]
	v_mfma_f32_16x16x32_bf16 v[76:79], v[146:149], v[216:219], v[76:79]
	v_mfma_f32_16x16x32_bf16 v[72:75], v[154:157], v[216:219], v[72:75]
	s_setprio 0
	s_setprio 1
	v_mfma_f32_16x16x32_bf16 v[116:119], v[158:161], v[188:191], v[116:119]
	v_mfma_f32_16x16x32_bf16 v[112:115], v[166:169], v[188:191], v[112:115]
	v_mfma_f32_16x16x32_bf16 v[100:103], v[158:161], v[196:199], v[100:103]
	v_mfma_f32_16x16x32_bf16 v[96:99], v[166:169], v[196:199], v[96:99]
	v_mfma_f32_16x16x32_bf16 v[84:87], v[158:161], v[204:207], v[84:87]
	v_mfma_f32_16x16x32_bf16 v[80:83], v[166:169], v[204:207], v[80:83]
	v_mfma_f32_16x16x32_bf16 v[68:71], v[158:161], v[212:215], v[68:71]
	v_mfma_f32_16x16x32_bf16 v[64:67], v[166:169], v[212:215], v[64:67]
	v_mfma_f32_16x16x32_bf16 v[116:119], v[162:165], v[192:195], v[116:119]
	v_mfma_f32_16x16x32_bf16 v[112:115], v[170:173], v[192:195], v[112:115]
	v_mfma_f32_16x16x32_bf16 v[100:103], v[162:165], v[200:203], v[100:103]
	v_mfma_f32_16x16x32_bf16 v[96:99], v[170:173], v[200:203], v[96:99]
	v_mfma_f32_16x16x32_bf16 v[84:87], v[162:165], v[208:211], v[84:87]
	v_mfma_f32_16x16x32_bf16 v[80:83], v[170:173], v[208:211], v[80:83]
	v_mfma_f32_16x16x32_bf16 v[68:71], v[162:165], v[216:219], v[68:71]
	v_mfma_f32_16x16x32_bf16 v[64:67], v[170:173], v[216:219], v[64:67]
	s_setprio 0
	s_barrier
	s_add_i32 s53, s53, s43
	s_add_u32 s38, s6, 0x80
	s_addc_u32 s39, s7, 0
	s_mov_b32 m0, s53
	ds_read_b128 v[188:191], v145 offset:16384
	ds_read_b128 v[192:195], v145 offset:17408
	ds_read_b128 v[196:199], v145 offset:18432
	ds_read_b128 v[200:203], v145 offset:19456
	ds_read_b128 v[204:207], v145 offset:20480
	ds_read_b128 v[208:211], v145 offset:21504
	ds_read_b128 v[212:215], v145 offset:22528
	ds_read_b128 v[216:219], v145 offset:23552
	global_load_lds_dwordx4 v130, s[6:7]
	s_add_i32 m0, s53, 0x2000
	s_add_u32 s80, s6, 0x100000
	s_addc_u32 s81, s7, 0
	s_add_i32 s53, s90, s43
	global_load_lds_dwordx4 v134, s[6:7]
	s_mov_b32 m0, s53
	s_nop 0
	global_load_lds_dwordx4 v130, s[80:81]
	s_add_i32 m0, s53, 0x2000
	s_nop 0
	global_load_lds_dwordx4 v134, s[80:81]
	s_waitcnt vmcnt(6)
	s_waitcnt lgkmcnt(0)
	s_barrier
	s_setprio 1
	s_waitcnt lgkmcnt(0)
	v_mfma_f32_16x16x32_bf16 v[60:63], v[140:143], v[188:191], v[60:63]
	v_mfma_f32_16x16x32_bf16 v[56:59], v[150:153], v[188:191], v[56:59]
	v_mfma_f32_16x16x32_bf16 v[44:47], v[140:143], v[196:199], v[44:47]
	v_mfma_f32_16x16x32_bf16 v[40:43], v[150:153], v[196:199], v[40:43]
	v_mfma_f32_16x16x32_bf16 v[28:31], v[140:143], v[204:207], v[28:31]
	v_mfma_f32_16x16x32_bf16 v[24:27], v[150:153], v[204:207], v[24:27]
	v_mfma_f32_16x16x32_bf16 v[12:15], v[140:143], v[212:215], v[12:15]
	v_mfma_f32_16x16x32_bf16 v[8:11], v[150:153], v[212:215], v[8:11]
	v_mfma_f32_16x16x32_bf16 v[60:63], v[146:149], v[192:195], v[60:63]
	v_mfma_f32_16x16x32_bf16 v[56:59], v[154:157], v[192:195], v[56:59]
	v_mfma_f32_16x16x32_bf16 v[44:47], v[146:149], v[200:203], v[44:47]
	v_mfma_f32_16x16x32_bf16 v[40:43], v[154:157], v[200:203], v[40:43]
	v_mfma_f32_16x16x32_bf16 v[28:31], v[146:149], v[208:211], v[28:31]
	v_mfma_f32_16x16x32_bf16 v[24:27], v[154:157], v[208:211], v[24:27]
	v_mfma_f32_16x16x32_bf16 v[12:15], v[146:149], v[216:219], v[12:15]
	v_mfma_f32_16x16x32_bf16 v[8:11], v[154:157], v[216:219], v[8:11]
	s_setprio 0
	s_setprio 1
	v_mfma_f32_16x16x32_bf16 v[52:55], v[158:161], v[188:191], v[52:55]
	v_mfma_f32_16x16x32_bf16 v[48:51], v[166:169], v[188:191], v[48:51]
	v_mfma_f32_16x16x32_bf16 v[36:39], v[158:161], v[196:199], v[36:39]
	v_mfma_f32_16x16x32_bf16 v[32:35], v[166:169], v[196:199], v[32:35]
	v_mfma_f32_16x16x32_bf16 v[20:23], v[158:161], v[204:207], v[20:23]
	v_mfma_f32_16x16x32_bf16 v[16:19], v[166:169], v[204:207], v[16:19]
	v_mfma_f32_16x16x32_bf16 v[4:7], v[158:161], v[212:215], v[4:7]
	v_mfma_f32_16x16x32_bf16 v[0:3], v[166:169], v[212:215], v[0:3]
	v_mfma_f32_16x16x32_bf16 v[52:55], v[162:165], v[192:195], v[52:55]
	v_mfma_f32_16x16x32_bf16 v[48:51], v[170:173], v[192:195], v[48:51]
	v_mfma_f32_16x16x32_bf16 v[36:39], v[162:165], v[200:203], v[36:39]
	v_mfma_f32_16x16x32_bf16 v[32:35], v[170:173], v[200:203], v[32:35]
	v_mfma_f32_16x16x32_bf16 v[20:23], v[162:165], v[208:211], v[20:23]
	v_mfma_f32_16x16x32_bf16 v[16:19], v[170:173], v[208:211], v[16:19]
	v_mfma_f32_16x16x32_bf16 v[4:7], v[162:165], v[216:219], v[4:7]
	v_mfma_f32_16x16x32_bf16 v[0:3], v[170:173], v[216:219], v[0:3]
	s_setprio 0
	s_barrier
	s_add_i32 s53, 0, 0x18000
	s_add_i32 s80, 0, 0x1c000
	v_add_u32_e32 v154, s53, v144
	v_add_u32_e32 v170, s80, v144
	ds_read_b128 v[140:143], v154
	ds_read_b128 v[146:149], v154 offset:1024
	ds_read_b128 v[150:153], v154 offset:2048
	ds_read_b128 v[154:157], v154 offset:3072
	ds_read_b128 v[158:161], v170
	ds_read_b128 v[162:165], v170 offset:1024
	ds_read_b128 v[166:169], v170 offset:2048
	ds_read_b128 v[170:173], v170 offset:3072
	s_mov_b32 m0, s49
	s_nop 0
	global_load_lds_dwordx4 v128, s[30:31]
	s_mov_b32 m0, s15
	s_nop 0
	global_load_lds_dwordx4 v132, s[30:31]
	s_add_u32 s30, s30, 0x100000
	s_addc_u32 s31, s31, 0
	s_mov_b32 m0, s36
	ds_read_b128 v[188:191], v145 offset:32768
	ds_read_b128 v[192:195], v145 offset:33792
	ds_read_b128 v[196:199], v145 offset:34816
	ds_read_b128 v[200:203], v145 offset:35840
	ds_read_b128 v[204:207], v145 offset:36864
	ds_read_b128 v[208:211], v145 offset:37888
	ds_read_b128 v[212:215], v145 offset:38912
	ds_read_b128 v[216:219], v145 offset:39936
	global_load_lds_dwordx4 v128, s[30:31]
	s_mov_b32 m0, s50
	s_nop 0
	global_load_lds_dwordx4 v132, s[30:31]
	s_waitcnt vmcnt(8)
	s_waitcnt lgkmcnt(0)
	s_barrier
	s_setprio 1
	s_waitcnt lgkmcnt(0)
	v_mfma_f32_16x16x32_bf16 v[124:127], v[140:143], v[188:191], v[124:127]
	v_mfma_f32_16x16x32_bf16 v[120:123], v[150:153], v[188:191], v[120:123]
	v_mfma_f32_16x16x32_bf16 v[108:111], v[140:143], v[196:199], v[108:111]
	v_mfma_f32_16x16x32_bf16 v[104:107], v[150:153], v[196:199], v[104:107]
	v_mfma_f32_16x16x32_bf16 v[92:95], v[140:143], v[204:207], v[92:95]
	v_mfma_f32_16x16x32_bf16 v[88:91], v[150:153], v[204:207], v[88:91]
	v_mfma_f32_16x16x32_bf16 v[76:79], v[140:143], v[212:215], v[76:79]
	v_mfma_f32_16x16x32_bf16 v[72:75], v[150:153], v[212:215], v[72:75]
	v_mfma_f32_16x16x32_bf16 v[124:127], v[146:149], v[192:195], v[124:127]
	v_mfma_f32_16x16x32_bf16 v[120:123], v[154:157], v[192:195], v[120:123]
	v_mfma_f32_16x16x32_bf16 v[108:111], v[146:149], v[200:203], v[108:111]
	v_mfma_f32_16x16x32_bf16 v[104:107], v[154:157], v[200:203], v[104:107]
	v_mfma_f32_16x16x32_bf16 v[92:95], v[146:149], v[208:211], v[92:95]
	v_mfma_f32_16x16x32_bf16 v[88:91], v[154:157], v[208:211], v[88:91]
	v_mfma_f32_16x16x32_bf16 v[76:79], v[146:149], v[216:219], v[76:79]
	v_mfma_f32_16x16x32_bf16 v[72:75], v[154:157], v[216:219], v[72:75]
	s_setprio 0
	s_setprio 1
	v_mfma_f32_16x16x32_bf16 v[116:119], v[158:161], v[188:191], v[116:119]
	v_mfma_f32_16x16x32_bf16 v[112:115], v[166:169], v[188:191], v[112:115]
	v_mfma_f32_16x16x32_bf16 v[100:103], v[158:161], v[196:199], v[100:103]
	v_mfma_f32_16x16x32_bf16 v[96:99], v[166:169], v[196:199], v[96:99]
	v_mfma_f32_16x16x32_bf16 v[84:87], v[158:161], v[204:207], v[84:87]
	v_mfma_f32_16x16x32_bf16 v[80:83], v[166:169], v[204:207], v[80:83]
	v_mfma_f32_16x16x32_bf16 v[68:71], v[158:161], v[212:215], v[68:71]
	v_mfma_f32_16x16x32_bf16 v[64:67], v[166:169], v[212:215], v[64:67]
	v_mfma_f32_16x16x32_bf16 v[116:119], v[162:165], v[192:195], v[116:119]
	v_mfma_f32_16x16x32_bf16 v[112:115], v[170:173], v[192:195], v[112:115]
	v_mfma_f32_16x16x32_bf16 v[100:103], v[162:165], v[200:203], v[100:103]
	v_mfma_f32_16x16x32_bf16 v[96:99], v[170:173], v[200:203], v[96:99]
	v_mfma_f32_16x16x32_bf16 v[84:87], v[162:165], v[208:211], v[84:87]
	v_mfma_f32_16x16x32_bf16 v[80:83], v[170:173], v[208:211], v[80:83]
	v_mfma_f32_16x16x32_bf16 v[68:71], v[162:165], v[216:219], v[68:71]
	v_mfma_f32_16x16x32_bf16 v[64:67], v[170:173], v[216:219], v[64:67]
	s_setprio 0
	s_barrier
	s_add_i32 s30, s53, s43
	s_mov_b32 m0, s30
	ds_read_b128 v[188:191], v145 offset:49152
	ds_read_b128 v[192:195], v145 offset:50176
	ds_read_b128 v[196:199], v145 offset:51200
	ds_read_b128 v[200:203], v145 offset:52224
	ds_read_b128 v[204:207], v145 offset:53248
	ds_read_b128 v[208:211], v145 offset:54272
	ds_read_b128 v[212:215], v145 offset:55296
	ds_read_b128 v[216:219], v145 offset:56320
	global_load_lds_dwordx4 v130, s[38:39]
	s_add_i32 m0, s30, 0x2000
	s_add_u32 s6, s6, 0x100080
	s_addc_u32 s7, s7, 0
	s_add_i32 s30, s80, s43
	global_load_lds_dwordx4 v134, s[38:39]
	s_mov_b32 m0, s30
	s_nop 0
	global_load_lds_dwordx4 v130, s[6:7]
	s_add_i32 m0, s30, 0x2000
	s_nop 0
	global_load_lds_dwordx4 v134, s[6:7]
	s_waitcnt vmcnt(6)
	s_waitcnt lgkmcnt(0)
	s_barrier
	s_setprio 1
	s_waitcnt lgkmcnt(0)
	v_mfma_f32_16x16x32_bf16 v[60:63], v[140:143], v[188:191], v[60:63]
	v_mfma_f32_16x16x32_bf16 v[56:59], v[150:153], v[188:191], v[56:59]
	v_mfma_f32_16x16x32_bf16 v[44:47], v[140:143], v[196:199], v[44:47]
	s_add_i32 s79, s79, 2
	v_mfma_f32_16x16x32_bf16 v[40:43], v[150:153], v[196:199], v[40:43]
	v_mfma_f32_16x16x32_bf16 v[28:31], v[140:143], v[204:207], v[28:31]
	v_mfma_f32_16x16x32_bf16 v[24:27], v[150:153], v[204:207], v[24:27]
	s_add_u32 s4, s4, 0x100
	s_addc_u32 s5, s5, 0
	v_mfma_f32_16x16x32_bf16 v[12:15], v[140:143], v[212:215], v[12:15]
	v_mfma_f32_16x16x32_bf16 v[8:11], v[150:153], v[212:215], v[8:11]
	v_mfma_f32_16x16x32_bf16 v[60:63], v[146:149], v[192:195], v[60:63]
	s_add_u32 s55, s55, 0x100
	s_addc_u32 s78, s78, 0
	v_mfma_f32_16x16x32_bf16 v[56:59], v[154:157], v[192:195], v[56:59]
	v_mfma_f32_16x16x32_bf16 v[44:47], v[146:149], v[200:203], v[44:47]
	v_mfma_f32_16x16x32_bf16 v[40:43], v[154:157], v[200:203], v[40:43]
	s_add_u32 s6, s4, 0xfff00080
	s_addc_u32 s7, s5, -1
	v_mfma_f32_16x16x32_bf16 v[28:31], v[146:149], v[208:211], v[28:31]
	v_mfma_f32_16x16x32_bf16 v[24:27], v[154:157], v[208:211], v[24:27]
	v_mfma_f32_16x16x32_bf16 v[12:15], v[146:149], v[216:219], v[12:15]
	s_add_i32 s53, 0, 0x10000
	v_mfma_f32_16x16x32_bf16 v[8:11], v[154:157], v[216:219], v[8:11]
	s_setprio 0
	s_setprio 1
	v_mfma_f32_16x16x32_bf16 v[52:55], v[158:161], v[188:191], v[52:55]
	v_mfma_f32_16x16x32_bf16 v[48:51], v[166:169], v[188:191], v[48:51]
	s_cmp_eq_u32 s79, 60
	s_cselect_b32 s31, s27, s7
	s_cselect_b32 s30, s26, s6
	s_cselect_b32 s7, s29, s78
	s_cselect_b32 s6, s28, s55
	v_mfma_f32_16x16x32_bf16 v[36:39], v[158:161], v[196:199], v[36:39]
	v_mfma_f32_16x16x32_bf16 v[32:35], v[166:169], v[196:199], v[32:35]
	v_mfma_f32_16x16x32_bf16 v[20:23], v[158:161], v[204:207], v[20:23]
	s_add_i32 s90, 0, 0x14000
	v_mfma_f32_16x16x32_bf16 v[16:19], v[166:169], v[204:207], v[16:19]
	v_mfma_f32_16x16x32_bf16 v[4:7], v[158:161], v[212:215], v[4:7]
	v_mfma_f32_16x16x32_bf16 v[0:3], v[166:169], v[212:215], v[0:3]
	s_cmp_gt_u32 s79, 61
	v_mfma_f32_16x16x32_bf16 v[52:55], v[162:165], v[192:195], v[52:55]
	v_mfma_f32_16x16x32_bf16 v[48:51], v[170:173], v[192:195], v[48:51]
	v_mfma_f32_16x16x32_bf16 v[36:39], v[162:165], v[200:203], v[36:39]
	v_mfma_f32_16x16x32_bf16 v[32:35], v[170:173], v[200:203], v[32:35]
	v_mfma_f32_16x16x32_bf16 v[20:23], v[162:165], v[208:211], v[20:23]
	v_mfma_f32_16x16x32_bf16 v[16:19], v[170:173], v[208:211], v[16:19]
	v_mfma_f32_16x16x32_bf16 v[4:7], v[162:165], v[216:219], v[4:7]
	v_mfma_f32_16x16x32_bf16 v[0:3], v[170:173], v[216:219], v[0:3]
	s_setprio 0
	s_barrier
	s_cbranch_scc0 .Lk367_body
	s_and_b64 vcc, exec, s[24:25]
	s_cbranch_vccz .LBB0_370
	s_barrier
